# E4g + QKV GEMM epilogue: the two vmcnt(0) waits moved onto the rotary-load paths only (waves without rotary loads no longer wait for their first-half stores)
# baseline (speedup 1.0000x reference)
.LBB0_256:
	s_cmp_lt_i32 s16, 16
	s_cselect_b64 s[4:5], -1, 0
	s_and_b64 s[4:5], s[52:53], s[4:5]
	v_cndmask_b32_e64 v112, 0, 1, s[4:5]
	v_cmp_ne_u32_e64 s[6:7], 1, v112
	s_andn2_b64 vcc, exec, s[4:5]
	v_lshl_add_u32 v191, s30, 8, v1
	s_cbranch_vccnz .LBB0_258
	v_lshl_or_b32 v112, v191, 6, v187
	v_or_b32_e32 v114, 0x400, v112
	global_load_dwordx4 v[164:167], v112, s[42:43]
	global_load_dwordx4 v[160:163], v112, s[46:47]
	global_load_dwordx4 v[156:159], v114, s[42:43]
	global_load_dwordx4 v[152:155], v114, s[46:47]
	v_or_b32_e32 v114, 0x800, v112
	v_or_b32_e32 v112, 0xc00, v112
	global_load_dwordx4 v[148:151], v114, s[42:43]
	global_load_dwordx4 v[144:147], v114, s[46:47]
	global_load_dwordx4 v[140:143], v112, s[42:43]
	global_load_dwordx4 v[136:139], v112, s[46:47]
	s_waitcnt vmcnt(0)
	s_branch .LBB0_259

.LBB0_259:
	v_lshl_or_b32 v114, s16, 8, v189
	v_ashrrev_i32_e32 v115, 31, v114
	v_mov_b64_e32 v[192:193], s[40:41]
	v_pk_mul_f32 v[196:197], v[130:131], v[162:163]
	v_pk_mul_f32 v[198:199], v[128:129], v[160:161]
	v_pk_mul_f32 v[200:201], v[130:131], v[166:167]
	v_pk_mul_f32 v[202:203], v[128:129], v[164:165]
	v_mad_i64_i32 v[194:195], s[30:31], v191, s80, v[192:193]
	v_lshlrev_b64 v[114:115], 1, v[114:115]
	v_pk_fma_f32 v[198:199], v[132:133], v[164:165], v[198:199] neg_lo:[0,0,1] neg_hi:[0,0,1]
	v_pk_fma_f32 v[196:197], v[134:135], v[166:167], v[196:197] neg_lo:[0,0,1] neg_hi:[0,0,1]
	v_pk_fma_f32 v[202:203], v[132:133], v[160:161], v[202:203]
	v_pk_fma_f32 v[200:201], v[134:135], v[162:163], v[200:201]
	v_lshl_add_u64 v[194:195], v[194:195], 0, v[114:115]
	v_cndmask_b32_e64 v112, v134, v196, s[4:5]
	v_cndmask_b32_e64 v134, v135, v197, s[4:5]
	v_cndmask_b32_e64 v132, v132, v198, s[4:5]
	v_cndmask_b32_e64 v133, v133, v199, s[4:5]
	v_cndmask_b32_e64 v135, v130, v200, s[4:5]
	v_cndmask_b32_e64 v131, v131, v201, s[4:5]
	v_cndmask_b32_e64 v130, v128, v202, s[4:5]
	v_cndmask_b32_e64 v196, v129, v203, s[4:5]
	v_cvt_pk_bf16_f32 v128, v132, v133
	v_cvt_pk_bf16_f32 v129, v112, v134
	v_cvt_pk_bf16_f32 v130, v130, v196
	v_cvt_pk_bf16_f32 v131, v135, v131
	global_store_dwordx4 v[194:195], v[128:131], off
	v_pk_mul_f32 v[132:133], v[122:123], v[166:167]
	v_pk_mul_f32 v[134:135], v[120:121], v[164:165]
	v_pk_mul_f32 v[128:129], v[122:123], v[162:163]
	v_pk_mul_f32 v[130:131], v[120:121], v[160:161]
	v_pk_fma_f32 v[128:129], v[126:127], v[166:167], v[128:129] neg_lo:[0,0,1] neg_hi:[0,0,1]
	v_pk_fma_f32 v[134:135], v[124:125], v[160:161], v[134:135]
	v_pk_fma_f32 v[132:133], v[126:127], v[162:163], v[132:133]
	v_pk_fma_f32 v[130:131], v[124:125], v[164:165], v[130:131] neg_lo:[0,0,1] neg_hi:[0,0,1]
	v_cndmask_b32_e64 v112, v126, v128, s[4:5]
	v_cndmask_b32_e64 v126, v127, v129, s[4:5]
	v_cndmask_b32_e64 v127, v122, v132, s[4:5]
	v_cndmask_b32_e64 v123, v123, v133, s[4:5]
	v_cndmask_b32_e64 v122, v120, v134, s[4:5]
	v_cndmask_b32_e64 v124, v124, v130, s[4:5]
	v_cndmask_b32_e64 v125, v125, v131, s[4:5]
	v_cndmask_b32_e64 v128, v121, v135, s[4:5]
	v_cvt_pk_bf16_f32 v120, v124, v125
	v_cvt_pk_bf16_f32 v121, v112, v126
	v_cvt_pk_bf16_f32 v122, v122, v128
	v_cvt_pk_bf16_f32 v123, v127, v123
	global_store_dwordx4 v[194:195], v[120:123], off offset:256
	v_or_b32_e32 v112, 16, v191
	v_pk_mul_f32 v[124:125], v[106:107], v[152:153]
	v_pk_mul_f32 v[122:123], v[108:109], v[154:155]
	v_pk_mul_f32 v[126:127], v[108:109], v[158:159]
	v_pk_mul_f32 v[128:129], v[106:107], v[156:157]
	v_mad_i64_i32 v[120:121], s[30:31], v112, s80, v[192:193]
	v_pk_fma_f32 v[124:125], v[116:117], v[156:157], v[124:125] neg_lo:[0,0,1] neg_hi:[0,0,1]
	v_pk_fma_f32 v[122:123], v[118:119], v[158:159], v[122:123] neg_lo:[0,0,1] neg_hi:[0,0,1]
	v_pk_fma_f32 v[128:129], v[116:117], v[152:153], v[128:129]
	v_pk_fma_f32 v[126:127], v[118:119], v[154:155], v[126:127]
	v_lshl_add_u64 v[120:121], v[120:121], 0, v[114:115]
	v_cndmask_b32_e64 v112, v118, v122, s[4:5]
	v_cndmask_b32_e64 v118, v119, v123, s[4:5]
	v_cndmask_b32_e64 v116, v116, v124, s[4:5]
	v_cndmask_b32_e64 v117, v117, v125, s[4:5]
	v_cndmask_b32_e64 v119, v108, v126, s[4:5]
	v_cndmask_b32_e64 v109, v109, v127, s[4:5]
	v_cndmask_b32_e64 v108, v106, v128, s[4:5]
	v_cndmask_b32_e64 v122, v107, v129, s[4:5]
	v_cvt_pk_bf16_f32 v106, v116, v117
	v_cvt_pk_bf16_f32 v107, v112, v118
	v_cvt_pk_bf16_f32 v108, v108, v122
	v_cvt_pk_bf16_f32 v109, v119, v109
	global_store_dwordx4 v[120:121], v[106:109], off
	v_pk_mul_f32 v[116:117], v[100:101], v[158:159]
	v_pk_mul_f32 v[118:119], v[98:99], v[156:157]
	v_pk_mul_f32 v[106:107], v[100:101], v[154:155]
	v_pk_mul_f32 v[108:109], v[98:99], v[152:153]
	v_pk_fma_f32 v[106:107], v[104:105], v[158:159], v[106:107] neg_lo:[0,0,1] neg_hi:[0,0,1]
	v_pk_fma_f32 v[118:119], v[102:103], v[152:153], v[118:119]
	v_pk_fma_f32 v[116:117], v[104:105], v[154:155], v[116:117]
	v_pk_fma_f32 v[108:109], v[102:103], v[156:157], v[108:109] neg_lo:[0,0,1] neg_hi:[0,0,1]
	v_cndmask_b32_e64 v104, v104, v106, s[4:5]
	v_cndmask_b32_e64 v106, v100, v116, s[4:5]
	v_cndmask_b32_e64 v101, v101, v117, s[4:5]
	v_cndmask_b32_e64 v100, v98, v118, s[4:5]
	v_cndmask_b32_e64 v105, v105, v107, s[4:5]
	v_cndmask_b32_e64 v102, v102, v108, s[4:5]
	v_cndmask_b32_e64 v103, v103, v109, s[4:5]
	v_cndmask_b32_e64 v107, v99, v119, s[4:5]
	v_cvt_pk_bf16_f32 v98, v102, v103
	v_cvt_pk_bf16_f32 v99, v104, v105
	v_cvt_pk_bf16_f32 v100, v100, v107
	v_cvt_pk_bf16_f32 v101, v106, v101
	global_store_dwordx4 v[120:121], v[98:101], off offset:256
	v_pk_mul_f32 v[102:103], v[90:91], v[144:145]
	v_pk_mul_f32 v[104:105], v[92:93], v[150:151]
	v_or_b32_e32 v98, 32, v191
	v_pk_mul_f32 v[100:101], v[92:93], v[146:147]
	v_pk_mul_f32 v[106:107], v[90:91], v[148:149]
	v_mad_i64_i32 v[98:99], s[30:31], v98, s80, v[192:193]
	v_pk_fma_f32 v[102:103], v[94:95], v[148:149], v[102:103] neg_lo:[0,0,1] neg_hi:[0,0,1]
	v_pk_fma_f32 v[100:101], v[96:97], v[150:151], v[100:101] neg_lo:[0,0,1] neg_hi:[0,0,1]
	v_pk_fma_f32 v[106:107], v[94:95], v[144:145], v[106:107]
	v_pk_fma_f32 v[104:105], v[96:97], v[146:147], v[104:105]
	v_lshl_add_u64 v[98:99], v[98:99], 0, v[114:115]
	v_cndmask_b32_e64 v96, v96, v100, s[4:5]
	v_cndmask_b32_e64 v97, v97, v101, s[4:5]
	v_cndmask_b32_e64 v94, v94, v102, s[4:5]
	v_cndmask_b32_e64 v95, v95, v103, s[4:5]
	v_cndmask_b32_e64 v100, v92, v104, s[4:5]
	v_cndmask_b32_e64 v93, v93, v105, s[4:5]
	v_cndmask_b32_e64 v92, v90, v106, s[4:5]
	v_cndmask_b32_e64 v101, v91, v107, s[4:5]
	v_cvt_pk_bf16_f32 v90, v94, v95
	v_cvt_pk_bf16_f32 v91, v96, v97
	v_cvt_pk_bf16_f32 v92, v92, v101
	v_cvt_pk_bf16_f32 v93, v100, v93
	global_store_dwordx4 v[98:99], v[90:93], off
	v_pk_mul_f32 v[94:95], v[84:85], v[150:151]
	v_pk_mul_f32 v[96:97], v[82:83], v[148:149]
	v_pk_mul_f32 v[90:91], v[84:85], v[146:147]
	v_pk_mul_f32 v[92:93], v[82:83], v[144:145]
	v_pk_fma_f32 v[90:91], v[88:89], v[150:151], v[90:91] neg_lo:[0,0,1] neg_hi:[0,0,1]
	v_pk_fma_f32 v[96:97], v[86:87], v[144:145], v[96:97]
	v_pk_fma_f32 v[94:95], v[88:89], v[146:147], v[94:95]
	v_pk_fma_f32 v[92:93], v[86:87], v[148:149], v[92:93] neg_lo:[0,0,1] neg_hi:[0,0,1]
	v_cndmask_b32_e64 v88, v88, v90, s[4:5]
	v_cndmask_b32_e64 v90, v84, v94, s[4:5]
	v_cndmask_b32_e64 v85, v85, v95, s[4:5]
	v_cndmask_b32_e64 v84, v82, v96, s[4:5]
	v_cndmask_b32_e64 v89, v89, v91, s[4:5]
	v_cndmask_b32_e64 v86, v86, v92, s[4:5]
	v_cndmask_b32_e64 v87, v87, v93, s[4:5]
	v_cndmask_b32_e64 v91, v83, v97, s[4:5]
	v_cvt_pk_bf16_f32 v82, v86, v87
	v_cvt_pk_bf16_f32 v83, v88, v89
	v_cvt_pk_bf16_f32 v84, v84, v91
	v_cvt_pk_bf16_f32 v85, v90, v85
	global_store_dwordx4 v[98:99], v[82:85], off offset:256
	v_pk_mul_f32 v[88:89], v[76:77], v[142:143]
	v_pk_mul_f32 v[90:91], v[74:75], v[140:141]
	v_pk_mul_f32 v[84:85], v[76:77], v[138:139]
	v_or_b32_e32 v82, 48, v191
	v_pk_mul_f32 v[86:87], v[74:75], v[136:137]
	v_pk_fma_f32 v[84:85], v[80:81], v[142:143], v[84:85] neg_lo:[0,0,1] neg_hi:[0,0,1]
	v_pk_fma_f32 v[90:91], v[78:79], v[136:137], v[90:91]
	v_pk_fma_f32 v[88:89], v[80:81], v[138:139], v[88:89]
	v_mad_i64_i32 v[82:83], s[30:31], v82, s80, v[192:193]
	v_pk_fma_f32 v[86:87], v[78:79], v[140:141], v[86:87] neg_lo:[0,0,1] neg_hi:[0,0,1]
	v_cndmask_b32_e64 v80, v80, v84, s[4:5]
	v_cndmask_b32_e64 v84, v76, v88, s[4:5]
	v_cndmask_b32_e64 v77, v77, v89, s[4:5]
	v_cndmask_b32_e64 v76, v74, v90, s[4:5]
	v_lshl_add_u64 v[82:83], v[82:83], 0, v[114:115]
	v_cndmask_b32_e64 v81, v81, v85, s[4:5]
	v_cndmask_b32_e64 v78, v78, v86, s[4:5]
	v_cndmask_b32_e64 v79, v79, v87, s[4:5]
	v_cndmask_b32_e64 v85, v75, v91, s[4:5]
	v_cvt_pk_bf16_f32 v74, v78, v79
	v_cvt_pk_bf16_f32 v75, v80, v81
	v_cvt_pk_bf16_f32 v76, v76, v85
	v_cvt_pk_bf16_f32 v77, v84, v77
	global_store_dwordx4 v[82:83], v[74:77], off
	v_pk_mul_f32 v[78:79], v[68:69], v[142:143]
	v_pk_mul_f32 v[80:81], v[66:67], v[140:141]
	v_pk_mul_f32 v[74:75], v[68:69], v[138:139]
	v_pk_mul_f32 v[76:77], v[66:67], v[136:137]
	v_pk_fma_f32 v[74:75], v[72:73], v[142:143], v[74:75] neg_lo:[0,0,1] neg_hi:[0,0,1]
	v_pk_fma_f32 v[76:77], v[70:71], v[140:141], v[76:77] neg_lo:[0,0,1] neg_hi:[0,0,1]
	v_pk_fma_f32 v[80:81], v[70:71], v[136:137], v[80:81]
	v_pk_fma_f32 v[78:79], v[72:73], v[138:139], v[78:79]
	v_cndmask_b32_e64 v72, v72, v74, s[4:5]
	v_cndmask_b32_e64 v70, v70, v76, s[4:5]
	v_cndmask_b32_e64 v71, v71, v77, s[4:5]
	v_cndmask_b32_e64 v74, v68, v78, s[4:5]
	v_cndmask_b32_e64 v69, v69, v79, s[4:5]
	v_cndmask_b32_e64 v68, v66, v80, s[4:5]
	v_cvt_pk_bf16_f32 v66, v70, v71
	v_cndmask_b32_e64 v73, v73, v75, s[4:5]
	v_cndmask_b32_e64 v75, v67, v81, s[4:5]
	v_cvt_pk_bf16_f32 v67, v72, v73
	v_cvt_pk_bf16_f32 v68, v68, v75
	v_cvt_pk_bf16_f32 v69, v74, v69
	global_store_dwordx4 v[82:83], v[66:69], off offset:256
	s_and_b64 vcc, exec, s[6:7]
	s_nop 0
	v_add_u32_e32 v66, 0x80, v191
	s_cbranch_vccnz .LBB0_261
	v_lshl_or_b32 v67, v66, 6, v187
	v_add_u32_e32 v68, 0x400, v67
	global_load_dwordx4 v[164:167], v67, s[42:43]
	global_load_dwordx4 v[160:163], v67, s[46:47]
	global_load_dwordx4 v[156:159], v68, s[42:43]
	global_load_dwordx4 v[152:155], v68, s[46:47]
	v_add_u32_e32 v68, 0x800, v67
	v_add_u32_e32 v67, 0xc00, v67
	global_load_dwordx4 v[148:151], v68, s[42:43]
	global_load_dwordx4 v[144:147], v68, s[46:47]
	global_load_dwordx4 v[140:143], v67, s[42:43]
	global_load_dwordx4 v[136:139], v67, s[46:47]
	s_waitcnt vmcnt(0)
.LBB0_261:
	v_mov_b64_e32 v[68:69], s[40:41]
	v_pk_mul_f32 v[72:73], v[60:61], v[162:163]
	v_pk_mul_f32 v[74:75], v[58:59], v[160:161]
	v_pk_mul_f32 v[76:77], v[60:61], v[166:167]
	v_pk_mul_f32 v[78:79], v[58:59], v[164:165]
	v_mad_i64_i32 v[70:71], s[6:7], v66, s80, v[68:69]
	v_pk_fma_f32 v[74:75], v[62:63], v[164:165], v[74:75] neg_lo:[0,0,1] neg_hi:[0,0,1]
	v_pk_fma_f32 v[72:73], v[64:65], v[166:167], v[72:73] neg_lo:[0,0,1] neg_hi:[0,0,1]
	v_pk_fma_f32 v[78:79], v[62:63], v[160:161], v[78:79]
	v_pk_fma_f32 v[76:77], v[64:65], v[162:163], v[76:77]
	v_lshl_add_u64 v[70:71], v[70:71], 0, v[114:115]
	v_cndmask_b32_e64 v64, v64, v72, s[4:5]
	v_cndmask_b32_e64 v65, v65, v73, s[4:5]
	v_cndmask_b32_e64 v62, v62, v74, s[4:5]
	v_cndmask_b32_e64 v63, v63, v75, s[4:5]
	v_cndmask_b32_e64 v67, v60, v76, s[4:5]
	v_cndmask_b32_e64 v61, v61, v77, s[4:5]
	v_cndmask_b32_e64 v60, v58, v78, s[4:5]
	v_cndmask_b32_e64 v72, v59, v79, s[4:5]
	v_cvt_pk_bf16_f32 v58, v62, v63
	v_cvt_pk_bf16_f32 v59, v64, v65
	v_cvt_pk_bf16_f32 v60, v60, v72
	v_cvt_pk_bf16_f32 v61, v67, v61
	global_store_dwordx4 v[70:71], v[58:61], off
	v_pk_mul_f32 v[62:63], v[52:53], v[166:167]
	v_pk_mul_f32 v[64:65], v[50:51], v[164:165]
	v_pk_mul_f32 v[58:59], v[52:53], v[162:163]
	v_pk_mul_f32 v[60:61], v[50:51], v[160:161]
	v_pk_fma_f32 v[58:59], v[56:57], v[166:167], v[58:59] neg_lo:[0,0,1] neg_hi:[0,0,1]
	v_pk_fma_f32 v[64:65], v[54:55], v[160:161], v[64:65]
	v_pk_fma_f32 v[62:63], v[56:57], v[162:163], v[62:63]
	v_pk_fma_f32 v[60:61], v[54:55], v[164:165], v[60:61] neg_lo:[0,0,1] neg_hi:[0,0,1]
	v_cndmask_b32_e64 v56, v56, v58, s[4:5]
	v_cndmask_b32_e64 v58, v52, v62, s[4:5]
	v_cndmask_b32_e64 v53, v53, v63, s[4:5]
	v_cndmask_b32_e64 v52, v50, v64, s[4:5]
	v_cndmask_b32_e64 v57, v57, v59, s[4:5]
	v_cndmask_b32_e64 v54, v54, v60, s[4:5]
	v_cndmask_b32_e64 v55, v55, v61, s[4:5]
	v_cndmask_b32_e64 v59, v51, v65, s[4:5]
	v_cvt_pk_bf16_f32 v50, v54, v55
	v_cvt_pk_bf16_f32 v51, v56, v57
	v_cvt_pk_bf16_f32 v52, v52, v59
	v_cvt_pk_bf16_f32 v53, v58, v53
	global_store_dwordx4 v[70:71], v[50:53], off offset:256
	v_pk_mul_f32 v[54:55], v[42:43], v[152:153]
	v_pk_mul_f32 v[56:57], v[44:45], v[158:159]
	v_add_u32_e32 v50, 16, v66
	v_pk_mul_f32 v[52:53], v[44:45], v[154:155]
	v_pk_mul_f32 v[58:59], v[42:43], v[156:157]
	v_mad_i64_i32 v[50:51], s[6:7], v50, s80, v[68:69]
	v_pk_fma_f32 v[54:55], v[46:47], v[156:157], v[54:55] neg_lo:[0,0,1] neg_hi:[0,0,1]
	v_pk_fma_f32 v[52:53], v[48:49], v[158:159], v[52:53] neg_lo:[0,0,1] neg_hi:[0,0,1]
	v_pk_fma_f32 v[58:59], v[46:47], v[152:153], v[58:59]
	v_pk_fma_f32 v[56:57], v[48:49], v[154:155], v[56:57]
	v_lshl_add_u64 v[50:51], v[50:51], 0, v[114:115]
	v_cndmask_b32_e64 v48, v48, v52, s[4:5]
	v_cndmask_b32_e64 v49, v49, v53, s[4:5]
	v_cndmask_b32_e64 v46, v46, v54, s[4:5]
	v_cndmask_b32_e64 v47, v47, v55, s[4:5]
	v_cndmask_b32_e64 v52, v44, v56, s[4:5]
	v_cndmask_b32_e64 v45, v45, v57, s[4:5]
	v_cndmask_b32_e64 v44, v42, v58, s[4:5]
	v_cndmask_b32_e64 v53, v43, v59, s[4:5]
	v_cvt_pk_bf16_f32 v42, v46, v47
	v_cvt_pk_bf16_f32 v43, v48, v49
	v_cvt_pk_bf16_f32 v44, v44, v53
	v_cvt_pk_bf16_f32 v45, v52, v45
	global_store_dwordx4 v[50:51], v[42:45], off
	v_pk_mul_f32 v[46:47], v[36:37], v[158:159]
	v_pk_mul_f32 v[48:49], v[34:35], v[156:157]
	v_pk_mul_f32 v[42:43], v[36:37], v[154:155]
	v_pk_mul_f32 v[44:45], v[34:35], v[152:153]
	v_pk_fma_f32 v[42:43], v[40:41], v[158:159], v[42:43] neg_lo:[0,0,1] neg_hi:[0,0,1]
	v_pk_fma_f32 v[48:49], v[38:39], v[152:153], v[48:49]
	v_pk_fma_f32 v[46:47], v[40:41], v[154:155], v[46:47]
	v_pk_fma_f32 v[44:45], v[38:39], v[156:157], v[44:45] neg_lo:[0,0,1] neg_hi:[0,0,1]
	v_cndmask_b32_e64 v40, v40, v42, s[4:5]
	v_cndmask_b32_e64 v42, v36, v46, s[4:5]
	v_cndmask_b32_e64 v37, v37, v47, s[4:5]
	v_cndmask_b32_e64 v36, v34, v48, s[4:5]
	v_cndmask_b32_e64 v41, v41, v43, s[4:5]
	v_cndmask_b32_e64 v38, v38, v44, s[4:5]
	v_cndmask_b32_e64 v39, v39, v45, s[4:5]
	v_cndmask_b32_e64 v43, v35, v49, s[4:5]
	v_cvt_pk_bf16_f32 v34, v38, v39
	v_cvt_pk_bf16_f32 v35, v40, v41
	v_cvt_pk_bf16_f32 v36, v36, v43
	v_cvt_pk_bf16_f32 v37, v42, v37
	global_store_dwordx4 v[50:51], v[34:37], off offset:256
	v_pk_mul_f32 v[38:39], v[26:27], v[144:145]
	v_pk_mul_f32 v[40:41], v[28:29], v[150:151]
	v_add_u32_e32 v34, 32, v66
	v_pk_mul_f32 v[36:37], v[28:29], v[146:147]
	v_pk_mul_f32 v[42:43], v[26:27], v[148:149]
	v_mad_i64_i32 v[34:35], s[6:7], v34, s80, v[68:69]
	v_pk_fma_f32 v[38:39], v[30:31], v[148:149], v[38:39] neg_lo:[0,0,1] neg_hi:[0,0,1]
	v_pk_fma_f32 v[36:37], v[32:33], v[150:151], v[36:37] neg_lo:[0,0,1] neg_hi:[0,0,1]
	v_pk_fma_f32 v[42:43], v[30:31], v[144:145], v[42:43]
	v_pk_fma_f32 v[40:41], v[32:33], v[146:147], v[40:41]
	v_lshl_add_u64 v[34:35], v[34:35], 0, v[114:115]
	v_cndmask_b32_e64 v32, v32, v36, s[4:5]
	v_cndmask_b32_e64 v33, v33, v37, s[4:5]
	v_cndmask_b32_e64 v30, v30, v38, s[4:5]
	v_cndmask_b32_e64 v31, v31, v39, s[4:5]
	v_cndmask_b32_e64 v36, v28, v40, s[4:5]
	v_cndmask_b32_e64 v29, v29, v41, s[4:5]
	v_cndmask_b32_e64 v28, v26, v42, s[4:5]
	v_cndmask_b32_e64 v37, v27, v43, s[4:5]
	v_cvt_pk_bf16_f32 v26, v30, v31
	v_cvt_pk_bf16_f32 v27, v32, v33
	v_cvt_pk_bf16_f32 v28, v28, v37
	v_cvt_pk_bf16_f32 v29, v36, v29
	global_store_dwordx4 v[34:35], v[26:29], off
	v_pk_mul_f32 v[30:31], v[20:21], v[150:151]
	v_pk_mul_f32 v[32:33], v[18:19], v[148:149]
	v_pk_mul_f32 v[26:27], v[20:21], v[146:147]
	v_pk_mul_f32 v[28:29], v[18:19], v[144:145]
	v_pk_fma_f32 v[26:27], v[24:25], v[150:151], v[26:27] neg_lo:[0,0,1] neg_hi:[0,0,1]
	v_pk_fma_f32 v[32:33], v[22:23], v[144:145], v[32:33]
	v_pk_fma_f32 v[30:31], v[24:25], v[146:147], v[30:31]
	v_pk_fma_f32 v[28:29], v[22:23], v[148:149], v[28:29] neg_lo:[0,0,1] neg_hi:[0,0,1]
	v_cndmask_b32_e64 v24, v24, v26, s[4:5]
	v_cndmask_b32_e64 v26, v20, v30, s[4:5]
	v_cndmask_b32_e64 v21, v21, v31, s[4:5]
	v_cndmask_b32_e64 v20, v18, v32, s[4:5]
	v_cndmask_b32_e64 v25, v25, v27, s[4:5]
	v_cndmask_b32_e64 v22, v22, v28, s[4:5]
	v_cndmask_b32_e64 v23, v23, v29, s[4:5]
	v_cndmask_b32_e64 v27, v19, v33, s[4:5]
	v_cvt_pk_bf16_f32 v18, v22, v23
	v_cvt_pk_bf16_f32 v19, v24, v25
	v_cvt_pk_bf16_f32 v20, v20, v27
	v_cvt_pk_bf16_f32 v21, v26, v21
	global_store_dwordx4 v[34:35], v[18:21], off offset:256
	v_pk_mul_f32 v[24:25], v[12:13], v[142:143]
	v_pk_mul_f32 v[26:27], v[10:11], v[140:141]
	v_pk_mul_f32 v[20:21], v[12:13], v[138:139]
	v_add_u32_e32 v18, 48, v66
	v_pk_mul_f32 v[22:23], v[10:11], v[136:137]
	v_pk_fma_f32 v[20:21], v[16:17], v[142:143], v[20:21] neg_lo:[0,0,1] neg_hi:[0,0,1]
	v_pk_fma_f32 v[26:27], v[14:15], v[136:137], v[26:27]
	v_pk_fma_f32 v[24:25], v[16:17], v[138:139], v[24:25]
	v_mad_i64_i32 v[18:19], s[6:7], v18, s80, v[68:69]
	v_pk_fma_f32 v[22:23], v[14:15], v[140:141], v[22:23] neg_lo:[0,0,1] neg_hi:[0,0,1]
	v_cndmask_b32_e64 v16, v16, v20, s[4:5]
	v_cndmask_b32_e64 v20, v12, v24, s[4:5]
	v_cndmask_b32_e64 v13, v13, v25, s[4:5]
	v_cndmask_b32_e64 v12, v10, v26, s[4:5]
	v_lshl_add_u64 v[18:19], v[18:19], 0, v[114:115]
	v_cndmask_b32_e64 v17, v17, v21, s[4:5]
	v_cndmask_b32_e64 v14, v14, v22, s[4:5]
	v_cndmask_b32_e64 v15, v15, v23, s[4:5]
	v_cndmask_b32_e64 v21, v11, v27, s[4:5]
	v_cvt_pk_bf16_f32 v10, v14, v15
	v_cvt_pk_bf16_f32 v11, v16, v17
	v_cvt_pk_bf16_f32 v12, v12, v21
	v_cvt_pk_bf16_f32 v13, v20, v13
	global_store_dwordx4 v[18:19], v[10:13], off
	v_pk_mul_f32 v[14:15], v[4:5], v[142:143]
	v_pk_mul_f32 v[16:17], v[2:3], v[140:141]
	v_pk_mul_f32 v[10:11], v[4:5], v[138:139]
	v_pk_mul_f32 v[12:13], v[2:3], v[136:137]
	v_pk_fma_f32 v[10:11], v[8:9], v[142:143], v[10:11] neg_lo:[0,0,1] neg_hi:[0,0,1]
	v_pk_fma_f32 v[12:13], v[6:7], v[140:141], v[12:13] neg_lo:[0,0,1] neg_hi:[0,0,1]
	v_pk_fma_f32 v[16:17], v[6:7], v[136:137], v[16:17]
	v_pk_fma_f32 v[14:15], v[8:9], v[138:139], v[14:15]
	v_cndmask_b32_e64 v8, v8, v10, s[4:5]
	v_cndmask_b32_e64 v6, v6, v12, s[4:5]
	v_cndmask_b32_e64 v7, v7, v13, s[4:5]
	v_cndmask_b32_e64 v10, v4, v14, s[4:5]
	v_cndmask_b32_e64 v5, v5, v15, s[4:5]
	v_cndmask_b32_e64 v4, v2, v16, s[4:5]
	v_cvt_pk_bf16_f32 v2, v6, v7
	v_cndmask_b32_e64 v9, v9, v11, s[4:5]
	v_cndmask_b32_e64 v11, v3, v17, s[4:5]
	v_cvt_pk_bf16_f32 v3, v8, v9
	v_cvt_pk_bf16_f32 v4, v4, v11
	v_cvt_pk_bf16_f32 v5, v10, v5
	global_store_dwordx4 v[18:19], v[2:5], off offset:256
	s_and_b64 vcc, exec, s[8:9]
	s_mov_b64 s[4:5], -1
	v_add_u32_e32 v2, 0x80, v66
	s_cbranch_vccnz .LBB0_244
	s_andn2_b64 vcc, exec, s[14:15]
	s_cbranch_vccnz .LBB0_243
	s_barrier
	s_branch .LBB0_243
